# rope phase: wave-major worker index so each SIMD pairs a five-row wave with a four-row wave instead of ten versus eight rows per SIMD
# speedup vs baseline: 1.0064x; 1.0064x over previous
.Lgb3_done:
.LBB0_989:
	s_or_b64 exec, exec, s[2:3]
	v_mov_b32_e32 v0, v214
	v_readlane_b32 s3, v253, 0
	s_waitcnt lgkmcnt(0)
	s_barrier
	s_lshl_b32 s3, s3, 3
	v_readfirstlane_b32 s2, v0
	s_ashr_i32 s2, s2, 6
	s_lshr_b32 s14, s88, 3
	s_mul_i32 s2, s2, s14
	s_lshr_b32 s3, s3, 3
	s_add_i32 s2, s2, s3
	s_cmpk_gt_i32 s2, 0x23ff
	s_cbranch_scc1 .LBB0_1012
	v_and_b32_e32 v58, 63, v0
	v_lshlrev_b32_e32 v3, 3, v0
	v_bfe_u32 v1, v0, 2, 1
	v_and_b32_e32 v6, 24, v3
	v_mov_b32_e32 v3, s71
	v_mov_b32_e32 v5, s69
	v_cmp_gt_u32_e32 vcc, 48, v58
	v_lshlrev_b32_e32 v4, 6, v1
	v_lshlrev_b32_e32 v176, 8, v1
	v_cndmask_b32_e32 v9, v3, v5, vcc
	v_mov_b32_e32 v3, s70
	v_mov_b32_e32 v5, s68
	v_cmp_eq_u32_e64 s[6:7], 0, v1
	v_xor_b32_e32 v1, 1, v218
	v_cndmask_b32_e32 v8, v3, v5, vcc
	v_cmp_lt_i32_e32 vcc, v1, v219
	v_or_b32_e32 v3, 1, v6
	v_or_b32_e32 v5, 2, v6
	v_cndmask_b32_e32 v1, v218, v1, vcc
	v_lshlrev_b32_e32 v59, 2, v1
	v_xor_b32_e32 v1, 2, v218
	v_cmp_lt_i32_e32 vcc, v1, v219
	v_or_b32_e32 v7, 3, v6
	v_cvt_f32_ubyte0_e32 v3, v3
	v_cndmask_b32_e32 v1, v218, v1, vcc
	v_lshlrev_b32_e32 v60, 2, v1
	v_xor_b32_e32 v1, 4, v218
	v_cmp_lt_i32_e32 vcc, v1, v219
	v_cvt_f32_ubyte0_e32 v5, v5
	v_cvt_f32_ubyte0_e32 v7, v7
	v_cndmask_b32_e32 v1, v218, v1, vcc
	v_lshlrev_b32_e32 v61, 2, v1
	v_cvt_f32_ubyte0_e32 v1, v6
	v_mul_f32_e32 v1, 0xbed49a78, v1
	v_exp_f32_e32 v1, v1
	v_mul_f32_e32 v3, 0xbed49a78, v3
	v_mul_f32_e32 v5, 0xbed49a78, v5
	v_mul_f32_e32 v7, 0xbed49a78, v7
	v_exp_f32_e32 v3, v3
	v_exp_f32_e32 v5, v5
	v_exp_f32_e32 v7, v7
	v_mul_f32_e32 v62, 0.15915494, v1
	v_or_b32_e32 v1, 4, v6
	v_cvt_f32_ubyte0_e32 v1, v1
	v_mul_f32_e32 v1, 0xbed49a78, v1
	v_mul_f32_e32 v63, 0.15915494, v3
	v_mul_f32_e32 v64, 0.15915494, v5
	v_mul_f32_e32 v65, 0.15915494, v7
	v_exp_f32_e32 v1, v1
	v_or_b32_e32 v3, 5, v6
	v_or_b32_e32 v5, 6, v6
	v_or_b32_e32 v7, 7, v6
	v_cvt_f32_ubyte0_e32 v3, v3
	v_cvt_f32_ubyte0_e32 v5, v5
	v_cvt_f32_ubyte0_e32 v7, v7
	v_mul_f32_e32 v3, 0xbed49a78, v3
	v_mul_f32_e32 v5, 0xbed49a78, v5
	v_mul_f32_e32 v7, 0xbed49a78, v7
	s_lshl_b32 s90, s96, 7
	v_exp_f32_e32 v3, v3
	v_exp_f32_e32 v5, v5
	v_exp_f32_e32 v7, v7
	v_lshlrev_b32_e32 v2, 4, v0
	v_lshl_add_u64 v[8:9], s[90:91], 2, v[8:9]
	v_mul_f32_e32 v66, 0.15915494, v1
	v_lshlrev_b32_e32 v1, 5, v0
	v_and_b32_e32 v0, 1, v0
	v_lshl_add_u64 v[8:9], v[8:9], 0, v[176:177]
	v_lshlrev_b32_e32 v176, 2, v6
	v_lshlrev_b32_e32 v0, 4, v0
	s_movk_i32 s3, 0x7c0
	v_readlane_b32 s4, v253, 56
	v_and_b32_e32 v2, 0x380, v2
	v_lshl_add_u64 v[8:9], v[8:9], 0, v[176:177]
	v_and_or_b32 v176, v1, s3, v0
	v_readlane_b32 s5, v253, 57
	v_mul_f32_e32 v67, 0.15915494, v3
	v_mul_f32_e32 v68, 0.15915494, v5
	v_mul_f32_e32 v69, 0.15915494, v7
	v_lshlrev_b32_e32 v70, 3, v58
	v_lshl_add_u64 v[10:11], s[4:5], 0, v[176:177]
	v_lshlrev_b32_e32 v176, 1, v2
	v_lshlrev_b32_e32 v12, 1, v4
	v_lshlrev_b32_e32 v14, 1, v6
	s_branch .LBB0_992
